# phase 12 hipcc K-loop: cyclic K start, one start offset per XCD (blockIdx & 7), loop prefetch offset wrapped modulo the row
# speedup vs baseline: 1.0076x; 1.0076x over previous
.LBB0_916:
	s_or_b64 exec, exec, s[0:1]
	s_lshl_b32 s0, s40, 6
	s_and_b32 s6, s0, 0x1c0
	v_subrev_co_u32_e32 v12, vcc, 22, v64
	v_mov_b32_e32 v13, v65
	v_mov_b32_e32 v34, v199
	v_or_b32_e32 v32, s6, v100
	v_lshlrev_b64 v[8:9], 21, v[64:65]
	v_lshlrev_b64 v[12:13], 21, v[12:13]
	s_and_b32 s0, s33, 0x1c0
	v_lshl_add_u64 v[10:11], s[26:27], 0, v[8:9]
	v_lshlrev_b32_e32 v114, 4, v34
	v_lshl_add_u64 v[12:13], s[34:35], 0, v[12:13]
	v_lshlrev_b64 v[0:1], 1, v[0:1]
	v_add_u32_e32 v20, v32, v101
	v_add_u32_e32 v22, s0, v109
	v_add_u32_e32 v24, s0, v110
	v_add_u32_e32 v26, s0, v111
	v_add_u32_e32 v28, s0, v112
	v_readfirstlane_b32 s0, v114
	v_lshl_add_u64 v[8:9], s[94:95], 0, v[8:9]
	v_cndmask_b32_e32 v10, v12, v10, vcc
	v_cndmask_b32_e32 v11, v13, v11, vcc
	v_lshl_add_u64 v[18:19], v[66:67], 0, v[0:1]
	v_ashrrev_i32_e32 v21, 31, v20
	s_mov_b32 m0, s0
	v_cndmask_b32_e64 v9, v11, v9, s[4:5]
	v_cndmask_b32_e64 v8, v10, v8, s[4:5]
	v_lshlrev_b64 v[20:21], 12, v[20:21]
	s_barrier
	v_readlane_b32 s98, v242, 45
	s_and_b32 s98, s98, 7
	s_lshl_b32 s98, s98, 9
	s_mov_b32 s99, 0
	v_lshl_add_u64 v[18:19], v[18:19], 0, s[98:99]
	global_load_lds_dwordx4 v[18:19], off
	v_add_u32_e32 v18, 0x8000, v114
	v_lshl_add_u64 v[20:21], v[8:9], 0, v[20:21]
	v_readfirstlane_b32 s0, v18
	v_add_u32_e32 v18, 0x1000, v114
	v_lshlrev_b64 v[2:3], 1, v[2:3]
	v_add_u32_e32 v16, v32, v103
	v_lshl_add_u64 v[20:21], v[20:21], 0, v[80:81]
	s_mov_b32 m0, s0
	v_readfirstlane_b32 s0, v18
	v_lshl_add_u64 v[14:15], v[66:67], 0, v[2:3]
	v_ashrrev_i32_e32 v17, 31, v16
	v_lshl_add_u64 v[20:21], v[20:21], 0, s[98:99]
	global_load_lds_dwordx4 v[20:21], off
	s_mov_b32 m0, s0
	v_lshlrev_b64 v[16:17], 12, v[16:17]
	v_lshl_add_u64 v[14:15], v[14:15], 0, s[98:99]
	global_load_lds_dwordx4 v[14:15], off
	v_add_u32_e32 v14, 0x9000, v114
	v_lshl_add_u64 v[16:17], v[8:9], 0, v[16:17]
	v_readfirstlane_b32 s0, v14
	v_add_u32_e32 v14, 0x2000, v114
	v_lshlrev_b64 v[6:7], 1, v[6:7]
	v_add_u32_e32 v12, v32, v105
	v_lshl_add_u64 v[16:17], v[16:17], 0, v[80:81]
	s_mov_b32 m0, s0
	v_readfirstlane_b32 s0, v14
	v_lshl_add_u64 v[10:11], v[66:67], 0, v[6:7]
	v_ashrrev_i32_e32 v13, 31, v12
	v_lshl_add_u64 v[16:17], v[16:17], 0, s[98:99]
	global_load_lds_dwordx4 v[16:17], off
	s_mov_b32 m0, s0
	v_lshlrev_b64 v[12:13], 12, v[12:13]
	v_add_u32_e32 v32, v32, v107
	v_lshl_add_u64 v[10:11], v[10:11], 0, s[98:99]
	global_load_lds_dwordx4 v[10:11], off
	v_add_u32_e32 v10, 0xa000, v114
	v_lshl_add_u64 v[12:13], v[8:9], 0, v[12:13]
	v_ashrrev_i32_e32 v33, 31, v32
	v_readfirstlane_b32 s0, v10
	v_add_u32_e32 v10, 0x3000, v114
	v_lshl_add_u64 v[12:13], v[12:13], 0, v[80:81]
	v_lshlrev_b64 v[4:5], 1, v[4:5]
	v_lshlrev_b64 v[32:33], 12, v[32:33]
	s_mov_b32 m0, s0
	v_readfirstlane_b32 s0, v10
	v_add_u32_e32 v10, 0xb000, v114
	v_lshl_add_u64 v[30:31], v[66:67], 0, v[4:5]
	v_lshl_add_u64 v[32:33], v[8:9], 0, v[32:33]
	v_lshl_add_u64 v[12:13], v[12:13], 0, s[98:99]
	global_load_lds_dwordx4 v[12:13], off
	s_mov_b32 m0, s0
	v_readfirstlane_b32 s0, v10
	v_lshl_add_u64 v[32:33], v[32:33], 0, v[80:81]
	v_lshl_add_u64 v[30:31], v[30:31], 0, s[98:99]
	global_load_lds_dwordx4 v[30:31], off
	s_mov_b32 m0, s0
	v_and_b32_e32 v10, 15, v34
	v_lshl_add_u64 v[32:33], v[32:33], 0, s[98:99]
	global_load_lds_dwordx4 v[32:33], off
	v_lshrrev_b32_e32 v13, 1, v34
	v_and_or_b32 v10, v13, s39, v10
	v_lshrrev_b32_e32 v35, 4, v34
	v_bfe_u32 v11, v34, 4, 2
	v_bfe_u32 v12, v34, 1, 3
	v_lshlrev_b32_e32 v113, 7, v10
	v_lshlrev_b32_e32 v10, 7, v34
	v_ashrrev_i32_e32 v23, 31, v22
	v_ashrrev_i32_e32 v25, 31, v24
	v_ashrrev_i32_e32 v27, 31, v26
	v_ashrrev_i32_e32 v29, 31, v28
	v_and_b32_e32 v64, 0x2780, v10
	v_bitop3_b32 v10, v35, v12, 3 bitop3:0x6c
	v_bitop3_b32 v11, v11, v12, 4 bitop3:0x36
	v_lshlrev_b64 v[22:23], 12, v[22:23]
	v_lshlrev_b64 v[24:25], 12, v[24:25]
	v_lshlrev_b64 v[26:27], 12, v[26:27]
	v_lshlrev_b64 v[28:29], 12, v[28:29]
	v_lshlrev_b32_e32 v10, 3, v10
	v_lshlrev_b32_e32 v11, 3, v11
	v_lshl_add_u64 v[82:83], v[76:77], 0, v[0:1]
	v_lshl_add_u64 v[0:1], v[8:9], 0, v[78:79]
	v_mov_b32_e32 v12, 0
	v_lshl_add_u64 v[84:85], v[0:1], 0, v[22:23]
	v_lshl_add_u64 v[86:87], v[76:77], 0, v[2:3]
	v_lshl_add_u64 v[88:89], v[0:1], 0, v[24:25]
	v_lshl_add_u64 v[90:91], v[76:77], 0, v[6:7]
	v_lshl_add_u64 v[92:93], v[0:1], 0, v[26:27]
	v_lshl_add_u64 v[94:95], v[76:77], 0, v[4:5]
	v_lshl_add_u64 v[96:97], v[0:1], 0, v[28:29]
	s_mov_b64 s[0:1], 0
	s_mov_b32 s7, 0
	v_lshlrev_b32_e32 v116, 1, v10
	v_lshlrev_b32_e32 v115, 1, v11
	v_mov_b32_e32 v13, v12
	v_mov_b32_e32 v14, v12
	v_mov_b32_e32 v15, v12
	v_mov_b32_e32 v0, v12
	v_mov_b32_e32 v1, v12
	v_mov_b32_e32 v2, v12
	v_mov_b32_e32 v3, v12
	v_mov_b32_e32 v4, v12
	v_mov_b32_e32 v5, v12
	v_mov_b32_e32 v6, v12
	v_mov_b32_e32 v7, v12
	v_mov_b32_e32 v8, v12
	v_mov_b32_e32 v9, v12
	v_mov_b32_e32 v10, v12
	v_mov_b32_e32 v11, v12
	v_mov_b32_e32 v16, v12
	v_mov_b32_e32 v17, v12
	v_mov_b32_e32 v18, v12
	v_mov_b32_e32 v19, v12
	v_mov_b32_e32 v20, v12
	v_mov_b32_e32 v21, v12
	v_mov_b32_e32 v22, v12
	v_mov_b32_e32 v23, v12
	v_mov_b32_e32 v24, v12
	v_mov_b32_e32 v25, v12
	v_mov_b32_e32 v26, v12
	v_mov_b32_e32 v27, v12
	v_mov_b32_e32 v28, v12
	v_mov_b32_e32 v29, v12
	v_mov_b32_e32 v30, v12
	v_mov_b32_e32 v31, v12
	v_mov_b32_e32 v32, v12
	v_mov_b32_e32 v33, v12
	v_mov_b32_e32 v34, v12
	v_mov_b32_e32 v35, v12
	v_mov_b32_e32 v36, v12
	v_mov_b32_e32 v37, v12
	v_mov_b32_e32 v38, v12
	v_mov_b32_e32 v39, v12
	v_mov_b32_e32 v40, v12
	v_mov_b32_e32 v41, v12
	v_mov_b32_e32 v42, v12
	v_mov_b32_e32 v43, v12
	v_mov_b32_e32 v44, v12
	v_mov_b32_e32 v45, v12
	v_mov_b32_e32 v46, v12
	v_mov_b32_e32 v47, v12
	v_mov_b32_e32 v48, v12
	v_mov_b32_e32 v49, v12
	v_mov_b32_e32 v50, v12
	v_mov_b32_e32 v51, v12
	v_mov_b32_e32 v52, v12
	v_mov_b32_e32 v53, v12
	v_mov_b32_e32 v54, v12
	v_mov_b32_e32 v55, v12
	v_mov_b32_e32 v56, v12
	v_mov_b32_e32 v57, v12
	v_mov_b32_e32 v58, v12
	v_mov_b32_e32 v59, v12
	v_mov_b32_e32 v60, v12
	v_mov_b32_e32 v61, v12
	v_mov_b32_e32 v62, v12
	v_mov_b32_e32 v63, v12
.LBB0_917:
	s_add_u32 s100, s0, s98
	s_add_u32 s100, s100, 0x80
	s_and_b32 s100, s100, 0xfff
	s_sub_u32 s100, s100, 0x80
	s_subb_u32 s101, 0, 0
	s_and_b32 s8, s7, 0x2000
	s_xor_b32 s9, s8, 0x2000
	s_lshl_b32 s8, s8, 1
	v_lshl_add_u32 v117, s9, 1, v114
	v_add_u32_e32 v142, s8, v113
	v_or_b32_e32 v143, s8, v64
	v_readfirstlane_b32 s8, v117
	v_add_u32_e32 v134, 0x8000, v117
	v_lshl_add_u64 v[118:119], v[82:83], 0, s[100:101]
	v_add_u32_e32 v135, 0x1000, v117
	v_readfirstlane_b32 s9, v134
	s_mov_b32 m0, s8
	s_waitcnt vmcnt(0)
	s_waitcnt vmcnt(0) lgkmcnt(0)
	s_barrier
	v_lshl_add_u64 v[120:121], v[84:85], 0, s[100:101]
	v_add_u32_e32 v136, 0x9000, v117
	v_readfirstlane_b32 s10, v135
	global_load_lds_dwordx4 v[118:119], off
	s_mov_b32 m0, s9
	v_lshl_add_u64 v[122:123], v[86:87], 0, s[100:101]
	v_add_u32_e32 v137, 0x2000, v117
	v_readfirstlane_b32 s11, v136
	global_load_lds_dwordx4 v[120:121], off
	s_mov_b32 m0, s10
	v_lshl_add_u64 v[124:125], v[88:89], 0, s[100:101]
	v_add_u32_e32 v138, 0xa000, v117
	v_readfirstlane_b32 s12, v137
	global_load_lds_dwordx4 v[122:123], off
	s_mov_b32 m0, s11
	v_lshl_add_u64 v[126:127], v[90:91], 0, s[100:101]
	v_add_u32_e32 v139, 0x3000, v117
	v_readfirstlane_b32 s13, v138
	global_load_lds_dwordx4 v[124:125], off
	s_mov_b32 m0, s12
	v_lshl_add_u64 v[128:129], v[92:93], 0, s[100:101]
	v_add_u32_e32 v117, 0xb000, v117
	v_readfirstlane_b32 s14, v139
	global_load_lds_dwordx4 v[126:127], off
	s_mov_b32 m0, s13
	v_lshl_add_u64 v[130:131], v[94:95], 0, s[100:101]
	v_readfirstlane_b32 s15, v117
	global_load_lds_dwordx4 v[128:129], off
	s_mov_b32 m0, s14
	v_lshl_add_u64 v[132:133], v[96:97], 0, s[100:101]
	global_load_lds_dwordx4 v[130:131], off
	s_mov_b32 m0, s15
	v_add_u32_e32 v140, v143, v116
	global_load_lds_dwordx4 v[132:133], off
	v_add_u32_e32 v144, v142, v116
	ds_read_b128 v[118:121], v140 offset:32768
	ds_read_b128 v[122:125], v140 offset:34816
	ds_read_b128 v[126:129], v144
	ds_read_b128 v[130:133], v144 offset:2048
	ds_read_b128 v[134:137], v140 offset:36864
	ds_read_b128 v[138:141], v140 offset:38912
	s_waitcnt lgkmcnt(0)
	v_mfma_f32_16x16x32_bf16 v[60:63], v[118:121], v[126:129], v[60:63]
	v_add_u32_e32 v117, v142, v115
	v_add_u32_e32 v142, v143, v115
	s_add_u32 s0, s0, 0x80
	v_mfma_f32_16x16x32_bf16 v[56:59], v[122:125], v[126:129], v[56:59]
	s_addc_u32 s1, s1, 0
	s_addk_i32 s7, 0x2000
	s_cmpk_eq_i32 s0, 0xf80
	v_mfma_f32_16x16x32_bf16 v[52:55], v[134:137], v[126:129], v[52:55]
	v_mfma_f32_16x16x32_bf16 v[48:51], v[138:141], v[126:129], v[48:51]
	v_mfma_f32_16x16x32_bf16 v[44:47], v[118:121], v[130:133], v[44:47]
	v_mfma_f32_16x16x32_bf16 v[40:43], v[122:125], v[130:133], v[40:43]
	v_mfma_f32_16x16x32_bf16 v[36:39], v[134:137], v[130:133], v[36:39]
	v_mfma_f32_16x16x32_bf16 v[32:35], v[138:141], v[130:133], v[32:35]
	ds_read_b128 v[126:129], v144 offset:4096
	ds_read_b128 v[130:133], v144 offset:6144
	s_waitcnt lgkmcnt(0)
	v_mfma_f32_16x16x32_bf16 v[28:31], v[118:121], v[126:129], v[28:31]
	v_mfma_f32_16x16x32_bf16 v[24:27], v[122:125], v[126:129], v[24:27]
	v_mfma_f32_16x16x32_bf16 v[20:23], v[134:137], v[126:129], v[20:23]
	v_mfma_f32_16x16x32_bf16 v[16:19], v[138:141], v[126:129], v[16:19]
	v_mfma_f32_16x16x32_bf16 v[8:11], v[118:121], v[130:133], v[8:11]
	v_mfma_f32_16x16x32_bf16 v[4:7], v[122:125], v[130:133], v[4:7]
	ds_read_b128 v[118:121], v142 offset:32768
	ds_read_b128 v[122:125], v142 offset:34816
	v_mfma_f32_16x16x32_bf16 v[0:3], v[134:137], v[130:133], v[0:3]
	v_mfma_f32_16x16x32_bf16 v[12:15], v[138:141], v[130:133], v[12:15]
	ds_read_b128 v[126:129], v117
	ds_read_b128 v[130:133], v117 offset:2048
	ds_read_b128 v[134:137], v142 offset:36864
	ds_read_b128 v[138:141], v142 offset:38912
	s_waitcnt lgkmcnt(0)
	v_mfma_f32_16x16x32_bf16 v[60:63], v[118:121], v[126:129], v[60:63]
	v_mfma_f32_16x16x32_bf16 v[56:59], v[122:125], v[126:129], v[56:59]
	v_mfma_f32_16x16x32_bf16 v[52:55], v[134:137], v[126:129], v[52:55]
	v_mfma_f32_16x16x32_bf16 v[48:51], v[138:141], v[126:129], v[48:51]
	v_mfma_f32_16x16x32_bf16 v[44:47], v[118:121], v[130:133], v[44:47]
	v_mfma_f32_16x16x32_bf16 v[40:43], v[122:125], v[130:133], v[40:43]
	v_mfma_f32_16x16x32_bf16 v[36:39], v[134:137], v[130:133], v[36:39]
	v_mfma_f32_16x16x32_bf16 v[32:35], v[138:141], v[130:133], v[32:35]
	ds_read_b128 v[126:129], v117 offset:4096
	ds_read_b128 v[130:133], v117 offset:6144
	s_waitcnt lgkmcnt(0)
	v_mfma_f32_16x16x32_bf16 v[28:31], v[118:121], v[126:129], v[28:31]
	v_mfma_f32_16x16x32_bf16 v[24:27], v[122:125], v[126:129], v[24:27]
	v_mfma_f32_16x16x32_bf16 v[20:23], v[134:137], v[126:129], v[20:23]
	v_mfma_f32_16x16x32_bf16 v[16:19], v[138:141], v[126:129], v[16:19]
	v_mfma_f32_16x16x32_bf16 v[8:11], v[118:121], v[130:133], v[8:11]
	v_mfma_f32_16x16x32_bf16 v[4:7], v[122:125], v[130:133], v[4:7]
	v_mfma_f32_16x16x32_bf16 v[0:3], v[134:137], v[130:133], v[0:3]
	v_mfma_f32_16x16x32_bf16 v[12:15], v[138:141], v[130:133], v[12:15]
	s_cbranch_scc0 .LBB0_917
	v_add_u32_e32 v114, v64, v116
	s_waitcnt vmcnt(0)
	s_waitcnt vmcnt(0)
	s_barrier
	ds_read_b128 v[82:85], v114 offset:49152
	v_add_u32_e32 v124, v113, v116
	ds_read_b128 v[86:89], v114 offset:51200
	ds_read_b128 v[90:93], v124 offset:16384
	ds_read_b128 v[94:97], v124 offset:18432
	ds_read_b128 v[116:119], v114 offset:53248
	ds_read_b128 v[120:123], v114 offset:55296
	v_add_u32_e32 v113, v113, v115
	v_add_u32_e32 v64, v64, v115
	s_waitcnt lgkmcnt(3)
	v_mfma_f32_16x16x32_bf16 v[60:63], v[82:85], v[90:93], v[60:63]
	s_ashr_i32 s37, s36, 31
	s_lshl_b64 s[0:1], s[36:37], 17
	s_add_u32 s0, s2, s0
	v_mfma_f32_16x16x32_bf16 v[56:59], v[86:89], v[90:93], v[56:59]
	s_addc_u32 s1, s3, s1
	v_lshl_add_u64 v[114:115], s[0:1], 0, v[68:69]
	s_add_i32 s40, s40, s96
	s_waitcnt lgkmcnt(1)
	v_mfma_f32_16x16x32_bf16 v[52:55], v[116:119], v[90:93], v[52:55]
	v_cmp_ge_i32_e32 vcc, s40, v98
	s_and_b64 vcc, exec, vcc
	s_add_i32 s33, s33, s38
	s_waitcnt lgkmcnt(0)
	v_mfma_f32_16x16x32_bf16 v[48:51], v[120:123], v[90:93], v[48:51]
	ds_read_b128 v[90:93], v124 offset:20480
	ds_read_b128 v[124:127], v124 offset:22528
	ds_read_b128 v[128:131], v113 offset:16384
	ds_read_b128 v[132:135], v113 offset:18432
	ds_read_b128 v[136:139], v113 offset:20480
	ds_read_b128 v[140:143], v113 offset:22528
	ds_read_b128 v[144:147], v64 offset:49152
	ds_read_b128 v[148:151], v64 offset:51200
	s_waitcnt lgkmcnt(1)
	v_mfma_f32_16x16x32_bf16 v[60:63], v[144:147], v[128:131], v[60:63]
	v_mfma_f32_16x16x32_bf16 v[44:47], v[82:85], v[94:97], v[44:47]
	s_nop 6
	v_mul_f32_e32 v113, 0xbfb8aa3b, v61
	v_exp_f32_e32 v113, v113
	v_mfma_f32_16x16x32_bf16 v[40:43], v[86:89], v[94:97], v[40:43]
	v_mfma_f32_16x16x32_bf16 v[36:39], v[116:119], v[94:97], v[36:39]
	v_mfma_f32_16x16x32_bf16 v[32:35], v[120:123], v[94:97], v[32:35]
	ds_read_b128 v[94:97], v64 offset:53248
	ds_read_b128 v[152:155], v64 offset:55296
	v_mul_f32_e32 v64, 0xbfb8aa3b, v60
	v_exp_f32_e32 v64, v64
	v_mfma_f32_16x16x32_bf16 v[28:31], v[82:85], v[90:93], v[28:31]
	v_add_f32_e32 v64, 1.0, v64
	v_rcp_f32_e32 v156, v64
	v_add_f32_e32 v64, 1.0, v113
	v_rcp_f32_e32 v157, v64
	v_mul_f32_e32 v64, 0xbfb8aa3b, v62
	v_mfma_f32_16x16x32_bf16 v[24:27], v[86:89], v[90:93], v[24:27]
	v_exp_f32_e32 v64, v64
	v_pk_mul_f32 v[60:61], v[60:61], v[156:157]
	v_add_f32_e32 v64, 1.0, v64
	v_mfma_f32_16x16x32_bf16 v[20:23], v[116:119], v[90:93], v[20:23]
	v_mfma_f32_16x16x32_bf16 v[16:19], v[120:123], v[90:93], v[16:19]
	v_mul_f32_e32 v90, 0xbfb8aa3b, v63
	v_exp_f32_e32 v90, v90
	v_mfma_f32_16x16x32_bf16 v[8:11], v[82:85], v[124:127], v[8:11]
	v_rcp_f32_e32 v82, v64
	v_add_f32_e32 v64, 1.0, v90
	v_rcp_f32_e32 v83, v64
	s_waitcnt lgkmcnt(2)
	v_mfma_f32_16x16x32_bf16 v[56:59], v[148:151], v[128:131], v[56:59]
	s_waitcnt lgkmcnt(1)
	v_mfma_f32_16x16x32_bf16 v[52:55], v[94:97], v[128:131], v[52:55]
	s_waitcnt lgkmcnt(0)
	v_mfma_f32_16x16x32_bf16 v[48:51], v[152:155], v[128:131], v[48:51]
	s_nop 3
	v_mul_f32_e64 v56, v56, v60
	v_mul_f32_e64 v57, v57, v61
	v_pk_mul_f32 v[60:61], v[62:63], v[82:83]
	v_cvt_pk_bf16_f32 v56, v56, v57
	v_pk_mul_f32 v[58:59], v[58:59], v[60:61]
	v_or_b32_e32 v60, s6, v108
	v_lshlrev_b32_e32 v64, 1, v60
	v_cvt_pk_bf16_f32 v57, v58, v59
	v_lshl_add_u64 v[58:59], v[114:115], 0, v[64:65]
	global_store_dwordx2 v[58:59], v[56:57], off
	v_mul_f32_e32 v56, 0xbfb8aa3b, v52
	v_mul_f32_e32 v57, 0xbfb8aa3b, v53
	v_exp_f32_e32 v56, v56
	v_exp_f32_e32 v57, v57
	v_mul_f32_e32 v60, 0xbfb8aa3b, v54
	v_mul_f32_e32 v61, 0xbfb8aa3b, v55
	v_exp_f32_e32 v60, v60
	v_exp_f32_e32 v61, v61
	v_add_f32_e32 v56, 1.0, v56
	v_add_f32_e32 v57, 1.0, v57
	v_rcp_f32_e32 v56, v56
	v_rcp_f32_e32 v57, v57
	v_add_f32_e32 v60, 1.0, v60
	v_add_f32_e32 v61, 1.0, v61
	v_rcp_f32_e32 v60, v60
	v_rcp_f32_e32 v61, v61
	v_mfma_f32_16x16x32_bf16 v[44:47], v[144:147], v[132:135], v[44:47]
	v_mul_f32_e64 v52, v52, v56
	v_mul_f32_e64 v53, v53, v57
	v_pk_mul_f32 v[48:49], v[48:49], v[52:53]
	v_pk_mul_f32 v[52:53], v[54:55], v[60:61]
	v_cvt_pk_bf16_f32 v48, v48, v49
	v_pk_mul_f32 v[50:51], v[50:51], v[52:53]
	s_nop 1
	v_mul_f32_e32 v52, 0xbfb8aa3b, v46
	v_cvt_pk_bf16_f32 v49, v50, v51
	v_mul_f32_e32 v50, 0xbfb8aa3b, v44
	v_mul_f32_e32 v51, 0xbfb8aa3b, v45
	v_exp_f32_e32 v50, v50
	v_exp_f32_e32 v51, v51
	v_mul_f32_e32 v53, 0xbfb8aa3b, v47
	v_exp_f32_e32 v52, v52
	v_exp_f32_e32 v53, v53
	v_add_f32_e32 v50, 1.0, v50
	v_add_f32_e32 v51, 1.0, v51
	v_rcp_f32_e32 v50, v50
	v_rcp_f32_e32 v51, v51
	v_add_f32_e32 v52, 1.0, v52
	v_add_f32_e32 v53, 1.0, v53
	v_mfma_f32_16x16x32_bf16 v[40:43], v[148:151], v[132:135], v[40:43]
	v_rcp_f32_e32 v52, v52
	v_rcp_f32_e32 v53, v53
	v_pk_mul_f32 v[44:45], v[44:45], v[50:51]
	v_mfma_f32_16x16x32_bf16 v[36:39], v[94:97], v[132:135], v[36:39]
	global_store_dwordx2 v[58:59], v[48:49], off offset:32
	s_nop 2
	v_pk_mul_f32 v[40:41], v[40:41], v[44:45]
	v_pk_mul_f32 v[44:45], v[46:47], v[52:53]
	v_cvt_pk_bf16_f32 v40, v40, v41
	v_pk_mul_f32 v[42:43], v[42:43], v[44:45]
	v_mul_f32_e32 v46, 0xbfb8aa3b, v38
	v_cvt_pk_bf16_f32 v41, v42, v43
	v_mul_f32_e32 v42, 0xbfb8aa3b, v36
	v_exp_f32_e32 v44, v42
	v_mul_f32_e32 v42, 0xbfb8aa3b, v37
	v_exp_f32_e32 v45, v42
	v_mul_f32_e32 v47, 0xbfb8aa3b, v39
	v_exp_f32_e32 v46, v46
	v_exp_f32_e32 v47, v47
	v_add_f32_e32 v44, 1.0, v44
	v_add_f32_e32 v45, 1.0, v45
	v_rcp_f32_e32 v44, v44
	v_rcp_f32_e32 v45, v45
	v_add_f32_e32 v46, 1.0, v46
	v_add_f32_e32 v47, 1.0, v47
	v_mfma_f32_16x16x32_bf16 v[32:35], v[152:155], v[132:135], v[32:35]
	v_rcp_f32_e32 v46, v46
	v_rcp_f32_e32 v47, v47
	v_pk_mul_f32 v[36:37], v[36:37], v[44:45]
	v_mfma_f32_16x16x32_bf16 v[28:31], v[144:147], v[136:139], v[28:31]
	v_lshl_add_u64 v[48:49], s[0:1], 0, v[70:71]
	s_nop 2
	v_pk_mul_f32 v[32:33], v[32:33], v[36:37]
	v_pk_mul_f32 v[36:37], v[38:39], v[46:47]
	v_cvt_pk_bf16_f32 v32, v32, v33
	v_pk_mul_f32 v[34:35], v[34:35], v[36:37]
	v_lshl_add_u64 v[42:43], v[48:49], 0, v[64:65]
	v_cvt_pk_bf16_f32 v33, v34, v35
	v_mul_f32_e32 v34, 0xbfb8aa3b, v28
	v_mul_f32_e32 v35, 0xbfb8aa3b, v29
	v_exp_f32_e32 v34, v34
	v_exp_f32_e32 v35, v35
	global_store_dwordx2 v[42:43], v[32:33], off offset:32
	v_mfma_f32_16x16x32_bf16 v[24:27], v[148:151], v[136:139], v[24:27]
	v_add_f32_e32 v32, 1.0, v34
	v_add_f32_e32 v33, 1.0, v35
	v_mul_f32_e32 v34, 0xbfb8aa3b, v30
	v_mul_f32_e32 v35, 0xbfb8aa3b, v31
	v_exp_f32_e32 v34, v34
	v_exp_f32_e32 v35, v35
	v_rcp_f32_e32 v32, v32
	v_rcp_f32_e32 v33, v33
	v_add_f32_e32 v34, 1.0, v34
	v_add_f32_e32 v35, 1.0, v35
	v_rcp_f32_e32 v34, v34
	v_rcp_f32_e32 v35, v35
	v_mfma_f32_16x16x32_bf16 v[20:23], v[94:97], v[136:139], v[20:23]
	v_mul_f32_e64 v28, v28, v32
	v_mul_f32_e64 v29, v29, v33
	v_lshl_add_u64 v[36:37], s[0:1], 0, v[72:73]
	v_pk_mul_f32 v[24:25], v[24:25], v[28:29]
	v_pk_mul_f32 v[28:29], v[30:31], v[34:35]
	v_cvt_pk_bf16_f32 v24, v24, v25
	v_pk_mul_f32 v[26:27], v[26:27], v[28:29]
	s_nop 0
	v_mul_f32_e32 v30, 0xbfb8aa3b, v22
	v_cvt_pk_bf16_f32 v25, v26, v27
	v_mul_f32_e32 v26, 0xbfb8aa3b, v20
	v_exp_f32_e32 v28, v26
	v_mul_f32_e32 v26, 0xbfb8aa3b, v21
	v_exp_f32_e32 v29, v26
	v_mul_f32_e32 v31, 0xbfb8aa3b, v23
	v_exp_f32_e32 v30, v30
	v_exp_f32_e32 v31, v31
	v_add_f32_e32 v28, 1.0, v28
	v_add_f32_e32 v29, 1.0, v29
	v_rcp_f32_e32 v28, v28
	v_rcp_f32_e32 v29, v29
	v_add_f32_e32 v30, 1.0, v30
	v_add_f32_e32 v31, 1.0, v31
	v_mfma_f32_16x16x32_bf16 v[16:19], v[152:155], v[136:139], v[16:19]
	v_rcp_f32_e32 v30, v30
	v_rcp_f32_e32 v31, v31
	v_pk_mul_f32 v[20:21], v[20:21], v[28:29]
	v_mfma_f32_16x16x32_bf16 v[8:11], v[144:147], v[140:143], v[8:11]
	v_lshl_add_u64 v[26:27], v[36:37], 0, v[64:65]
	s_nop 2
	v_pk_mul_f32 v[16:17], v[16:17], v[20:21]
	v_pk_mul_f32 v[20:21], v[22:23], v[30:31]
	v_cvt_pk_bf16_f32 v16, v16, v17
	v_pk_mul_f32 v[18:19], v[18:19], v[20:21]
	v_mfma_f32_16x16x32_bf16 v[4:7], v[86:89], v[124:127], v[4:7]
	v_cvt_pk_bf16_f32 v17, v18, v19
	v_mul_f32_e32 v18, 0xbfb8aa3b, v8
	v_mul_f32_e32 v19, 0xbfb8aa3b, v9
	v_exp_f32_e32 v18, v18
	v_exp_f32_e32 v19, v19
	global_store_dwordx2 v[26:27], v[16:17], off offset:32
	v_mfma_f32_16x16x32_bf16 v[0:3], v[116:119], v[124:127], v[0:3]
	v_add_f32_e32 v16, 1.0, v18
	v_add_f32_e32 v17, 1.0, v19
	v_mul_f32_e32 v18, 0xbfb8aa3b, v10
	v_mul_f32_e32 v19, 0xbfb8aa3b, v11
	v_exp_f32_e32 v18, v18
	v_exp_f32_e32 v19, v19
	v_rcp_f32_e32 v16, v16
	v_rcp_f32_e32 v17, v17
	v_add_f32_e32 v18, 1.0, v18
	v_add_f32_e32 v19, 1.0, v19
	v_mfma_f32_16x16x32_bf16 v[4:7], v[148:151], v[140:143], v[4:7]
	v_rcp_f32_e32 v18, v18
	v_rcp_f32_e32 v19, v19
	v_pk_mul_f32 v[8:9], v[8:9], v[16:17]
	v_mfma_f32_16x16x32_bf16 v[0:3], v[94:97], v[140:143], v[0:3]
	v_lshl_add_u64 v[20:21], s[0:1], 0, v[74:75]
	s_nop 2
	v_pk_mul_f32 v[4:5], v[4:5], v[8:9]
	v_pk_mul_f32 v[8:9], v[10:11], v[18:19]
	v_cvt_pk_bf16_f32 v4, v4, v5
	v_pk_mul_f32 v[6:7], v[6:7], v[8:9]
	v_mul_f32_e32 v10, 0xbfb8aa3b, v2
	v_cvt_pk_bf16_f32 v5, v6, v7
	v_mul_f32_e32 v6, 0xbfb8aa3b, v0
	v_exp_f32_e32 v8, v6
	v_mul_f32_e32 v6, 0xbfb8aa3b, v1
	v_mul_f32_e32 v11, 0xbfb8aa3b, v3
	v_exp_f32_e32 v9, v6
	v_exp_f32_e32 v10, v10
	v_exp_f32_e32 v11, v11
	v_mfma_f32_16x16x32_bf16 v[12:15], v[120:123], v[124:127], v[12:15]
	v_add_f32_e32 v8, 1.0, v8
	v_add_f32_e32 v9, 1.0, v9
	v_add_f32_e32 v10, 1.0, v10
	v_add_f32_e32 v11, 1.0, v11
	v_rcp_f32_e32 v8, v8
	v_rcp_f32_e32 v9, v9
	v_rcp_f32_e32 v10, v10
	v_rcp_f32_e32 v11, v11
	v_mfma_f32_16x16x32_bf16 v[12:15], v[152:155], v[140:143], v[12:15]
	v_mul_f32_e64 v0, v0, v8
	v_mul_f32_e64 v1, v1, v9
	v_lshl_add_u64 v[6:7], v[20:21], 0, v[64:65]
	v_pk_mul_f32 v[2:3], v[2:3], v[10:11]
	global_store_dwordx2 v[42:43], v[40:41], off
	global_store_dwordx2 v[26:27], v[24:25], off
	s_nop 1
	v_pk_mul_f32 v[0:1], v[12:13], v[0:1]
	v_pk_mul_f32 v[2:3], v[14:15], v[2:3]
	v_cvt_pk_bf16_f32 v0, v0, v1
	v_cvt_pk_bf16_f32 v1, v2, v3
	global_store_dwordx2 v[6:7], v[4:5], off
	global_store_dwordx2 v[6:7], v[0:1], off offset:32
	s_cbranch_vccz .LBB0_908

	.amdhsa_kernel _Z14fwd_megakernel6Params
		.amdhsa_group_segment_fixed_size 65536
		.amdhsa_private_segment_fixed_size 0
		.amdhsa_kernarg_size 560
		.amdhsa_user_sgpr_count 2
		.amdhsa_user_sgpr_dispatch_ptr 0
		.amdhsa_user_sgpr_queue_ptr 0
		.amdhsa_user_sgpr_kernarg_segment_ptr 1
		.amdhsa_user_sgpr_dispatch_id 0
		.amdhsa_user_sgpr_kernarg_preload_length 0
		.amdhsa_user_sgpr_kernarg_preload_offset 0
		.amdhsa_user_sgpr_private_segment_size 0
		.amdhsa_uses_dynamic_stack 0
		.amdhsa_enable_private_segment 0
		.amdhsa_system_sgpr_workgroup_id_x 1
		.amdhsa_system_sgpr_workgroup_id_y 0
		.amdhsa_system_sgpr_workgroup_id_z 0
		.amdhsa_system_sgpr_workgroup_info 0
		.amdhsa_system_vgpr_workitem_id 2
		.amdhsa_next_free_vgpr 254
		.amdhsa_next_free_sgpr 102
		.amdhsa_accum_offset 256
		.amdhsa_reserve_vcc 1
		.amdhsa_float_round_mode_32 0
		.amdhsa_float_round_mode_16_64 0
		.amdhsa_float_denorm_mode_32 3
		.amdhsa_float_denorm_mode_16_64 3
		.amdhsa_dx10_clamp 1
		.amdhsa_ieee_mode 1
		.amdhsa_fp16_overflow 0
		.amdhsa_tg_split 0
		.amdhsa_exception_fp_ieee_invalid_op 0
		.amdhsa_exception_fp_denorm_src 0
		.amdhsa_exception_fp_ieee_div_zero 0
		.amdhsa_exception_fp_ieee_overflow 0
		.amdhsa_exception_fp_ieee_underflow 0
		.amdhsa_exception_fp_ieee_inexact 0
		.amdhsa_exception_int_div_zero 0
	.end_amdhsa_kernel

amdhsa.kernels:
  - .agpr_count:     0
    .args:
      - .offset:         0
        .size:           304
        .value_kind:     by_value
      - .offset:         304
        .size:           4
        .value_kind:     hidden_block_count_x
      - .offset:         308
        .size:           4
        .value_kind:     hidden_block_count_y
      - .offset:         312
        .size:           4
        .value_kind:     hidden_block_count_z
      - .offset:         316
        .size:           2
        .value_kind:     hidden_group_size_x
      - .offset:         318
        .size:           2
        .value_kind:     hidden_group_size_y
      - .offset:         320
        .size:           2
        .value_kind:     hidden_group_size_z
      - .offset:         322
        .size:           2
        .value_kind:     hidden_remainder_x
      - .offset:         324
        .size:           2
        .value_kind:     hidden_remainder_y
      - .offset:         326
        .size:           2
        .value_kind:     hidden_remainder_z
      - .offset:         344
        .size:           8
        .value_kind:     hidden_global_offset_x
      - .offset:         352
        .size:           8
        .value_kind:     hidden_global_offset_y
      - .offset:         360
        .size:           8
        .value_kind:     hidden_global_offset_z
      - .offset:         368
        .size:           2
        .value_kind:     hidden_grid_dims
      - .offset:         392
        .size:           8
        .value_kind:     hidden_multigrid_sync_arg
    .group_segment_fixed_size: 65536
    .kernarg_segment_align: 8
    .kernarg_segment_size: 560
    .language:       OpenCL C
    .language_version:
      - 2
      - 0
    .max_flat_workgroup_size: 256
    .name:           _Z14fwd_megakernel6Params
    .private_segment_fixed_size: 0
    .sgpr_count:     108
    .sgpr_spill_count: 65
    .symbol:         _Z14fwd_megakernel6Params.kd
    .uniform_work_group_size: 1
    .uses_dynamic_stack: false
    .vgpr_count:     254
    .vgpr_spill_count: 0
    .wavefront_size: 64
